# block-0 control-word zeroing as 16B write-through stores; release fence before flag publish
# baseline (speedup 1.0000x reference)
_Z8mega_fwd4Args:
	s_load_dwordx8 s[4:11], s[0:1], 0x40
	v_and_b32_e32 v194, 0x3ff, v0
	v_writelane_b32 v252, s2, 0
	s_load_dwordx4 s[28:31], s[0:1], 0x60
	s_load_dwordx2 s[2:3], s[0:1], 0x70
	v_mov_b32_e32 v1, v194
	s_waitcnt lgkmcnt(0)
	v_writelane_b32 v252, s4, 1
	v_cmp_gt_u32_e32 vcc, 8, v194
	s_nop 0
	v_writelane_b32 v252, s5, 2
	v_writelane_b32 v252, s6, 3
	v_writelane_b32 v252, s7, 4
	v_writelane_b32 v252, s8, 5
	v_writelane_b32 v252, s9, 6
	v_writelane_b32 v252, s10, 7
	v_writelane_b32 v252, s11, 8
	v_writelane_b32 v252, s2, 9
	s_add_u32 s8, s0, 0x78
	s_addc_u32 s9, s1, 0
	v_writelane_b32 v252, s3, 10
	s_load_dword s3, s[0:1], 0x78
	s_load_dwordx2 s[6:7], s[0:1], 0x7c
	s_and_saveexec_b64 s[4:5], vcc
	v_lshl_add_u32 v1, v194, 2, 0
	v_add_u32_e32 v1, 0x20100, v1
	v_mov_b32_e32 v2, 0
	ds_write_b32 v1, v2
	s_or_b64 exec, exec, s[4:5]
	s_load_dwordx16 s[12:27], s[0:1], 0x0
	s_add_u32 s0, s30, 0x200000
	s_waitcnt lgkmcnt(0)
	s_barrier
	v_writelane_b32 v252, s12, 11
	s_nop 1
	v_writelane_b32 v252, s13, 12
	v_writelane_b32 v252, s14, 13
	v_writelane_b32 v252, s15, 14
	v_writelane_b32 v252, s16, 15
	v_writelane_b32 v252, s17, 16
	v_writelane_b32 v252, s18, 17
	v_writelane_b32 v252, s19, 18
	v_writelane_b32 v252, s20, 19
	v_writelane_b32 v252, s21, 20
	v_writelane_b32 v252, s22, 21
	v_writelane_b32 v252, s23, 22
	v_writelane_b32 v252, s24, 23
	v_writelane_b32 v252, s25, 24
	v_writelane_b32 v252, s26, 25
	v_writelane_b32 v252, s27, 26
	v_writelane_b32 v252, s0, 27
	s_addc_u32 s0, s31, 0
	v_writelane_b32 v252, s0, 28
	s_add_u32 s0, s30, 0x7a00000
	v_writelane_b32 v252, s0, 29
	s_addc_u32 s0, s31, 0
	v_writelane_b32 v252, s0, 30
	s_nop 0
	v_readlane_b32 s4, v252, 9
	v_readlane_b32 s5, v252, 10
	s_cmp_lt_i32 s4, 1
	s_cselect_b64 s[0:1], -1, 0
	s_cmp_gt_i32 s5, 0
	s_cselect_b64 s[4:5], -1, 0
	s_and_b64 s[10:11], s[0:1], s[4:5]
	s_andn2_b64 vcc, exec, s[10:11]
	s_cbranch_vccnz .LBB0_96
	v_readlane_b32 s0, v252, 0
	v_mov_b32_e32 v34, v194
	s_cmp_eq_u32 s0, 0
	s_movk_i32 s4, 0x4000
	s_cselect_b64 s[0:1], -1, 0
	v_cmp_gt_i32_e32 vcc, s4, v34
	v_readfirstlane_b32 s2, v34
	s_and_b64 s[4:5], s[0:1], vcc
	s_and_saveexec_b64 s[0:1], s[4:5]
	s_cbranch_execz .LBB0_11
	v_lshlrev_b32_e32 v2, 4, v34
	v_mov_b32_e32 v4, 0
	v_mov_b32_e32 v5, 0
	v_mov_b32_e32 v6, 0
	v_mov_b32_e32 v7, 0
	s_mov_b64 s[12:13], s[30:31]
	global_store_dwordx4 v2, v[4:7], s[12:13] sc1
	s_add_u32 s12, s12, 0x2000
	s_addc_u32 s13, s13, 0
	global_store_dwordx4 v2, v[4:7], s[12:13] sc1
	s_add_u32 s12, s12, 0x2000
	s_addc_u32 s13, s13, 0
	global_store_dwordx4 v2, v[4:7], s[12:13] sc1
	s_add_u32 s12, s12, 0x2000
	s_addc_u32 s13, s13, 0
	global_store_dwordx4 v2, v[4:7], s[12:13] sc1
	s_add_u32 s12, s12, 0x2000
	s_addc_u32 s13, s13, 0
	global_store_dwordx4 v2, v[4:7], s[12:13] sc1
	s_add_u32 s12, s12, 0x2000
	s_addc_u32 s13, s13, 0
	global_store_dwordx4 v2, v[4:7], s[12:13] sc1
	s_add_u32 s12, s12, 0x2000
	s_addc_u32 s13, s13, 0
	global_store_dwordx4 v2, v[4:7], s[12:13] sc1
	s_add_u32 s12, s12, 0x2000
	s_addc_u32 s13, s13, 0
	global_store_dwordx4 v2, v[4:7], s[12:13] sc1
.LBB0_11:
	s_or_b64 exec, exec, s[0:1]
	v_readlane_b32 s0, v252, 0
	s_cmp_lg_u32 s0, 0
	s_cbranch_scc1 .Lflag_skip
	s_waitcnt vmcnt(0)
	s_barrier
	v_cmp_eq_u32_e32 vcc, 0, v34
	s_and_saveexec_b64 s[4:5], vcc
	s_cbranch_execz .Lflag_w
	s_add_u32 s12, s30, 0xc000
	s_addc_u32 s13, s31, 0
	buffer_wbl2 sc1
	s_waitcnt vmcnt(0)
	v_mov_b32_e32 v2, 0x600df1a6
	v_mov_b32_e32 v3, 0
	global_store_dword v3, v2, s[12:13] sc1
	s_waitcnt vmcnt(0)
